# EpiRes epilogue prefetches two row groups up front; SG unit loop loads hoisted to loop top with counted waits
# speedup vs baseline: 1.0542x; 1.0172x over previous
; __device__ __forceinline__ unsigned cvt_pk_bf16(float lo, float hi) { const f2_t v = {lo, hi}; const bf2_t b = __builtin_convertvector(v, bf2_t); return __builtin_bit_cast(unsigned, b); }
; __device__ __forceinline__ f32x4 mfma16(bf16x8 a, bf16x8 b, f32x4 c) { return __builtin_amdgcn_mfma_f32_16x16x32_bf16(a, b, c, 0, 0, 0); }
; __device__ void sg_phase(int wv, const Params& p, int jl, unsigned char* lds) {
;     ...
;     for (int unit = blockIdx.x; unit < 2048; unit += gridDim.x) {
;         const int ch = unit >> 3, g = unit & 7, t0 = ch * 128;
;         if (tid < 128) rsL[tid] = 1.0f / sqrtf((float)vss[t0 + tid] * SSKI + EPSN);
;         __syncthreads();
;         const float* ws = p.a_w_s + ((size_t)jl * 8 + g) * 128 * 128;
; #pragma unroll
;         for (int ps = 0; ps < 8; ++ps) { const int idx = tid + ps * NTHR, t = idx >> 5, s4 = (idx & 31) * 4;
;             const f32x4 wv = *(const f32x4*)(ws + t * 128 + s4); const f32x4 r4 = *(const f32x4*)(rsL + s4); const f32x4 x = wv * r4;
;             u32x2 pk; pk.x = cvt_pk_bf16(x[0], x[1]); pk.y = cvt_pk_bf16(x[2], x[3]); *(u32x2*)(WsL + t * PW + s4) = pk; }
; #pragma unroll
;         for (int ps = 0; ps < 4; ++ps) { const int idx = tid + ps * NTHR, s = idx & 127, d8 = (idx >> 7) * 8;
;             const bf16x8 v = *(const bf16x8*)(uv + (size_t)(t0 + s) * 2048 + 1024 + g * 128 + d8);
; #pragma unroll
;             for (int e = 0; e < 8; ++e) VTL[(d8 + e) * PW + s] = (bf16_t)v[e]; }
;         __syncthreads();
;         bf16x8 af[4];
; #pragma unroll
;         for (int kk = 0; kk < 4; ++kk) af[kk] = *(const bf16x8*)(WsL + (16 * w + lr) * PW + 32 * kk + 8 * lq);
;         const int tok = t0 + 16 * w + lr; const float bs = p.a_b_s[((size_t)jl * 8 + g) * 128 + 16 * w + lr];
; #pragma unroll
;         for (int db = 0; db < 8; ++db) { f32x4 acc = {0, 0, 0, 0};
; #pragma unroll
;             for (int kk = 0; kk < 4; ++kk) { const bf16x8 bf = *(const bf16x8*)(VTL + (16 * db + lr) * PW + 32 * kk + 8 * lq); acc = mfma16(bf, af[kk], acc); }
;             const int col = g * 128 + 16 * db + 4 * lq; const f32x4 gv = *(const f32x4*)(p.a_g_v + jl * DM + col);
;             bf16_t* up = uv + (size_t)tok * 2048 + col; const u32x2 uu = *(const u32x2*)up;
.LBB0_287:
	s_or_b64 exec, exec, s[16:17]
	s_and_b32 s6, s22, 0x380
	s_or_b32 s7, s20, s6
	s_lshl_b32 s36, s7, 9
	v_lshl_add_u64 v[10:11], v[42:43], 0, s[36:37]
	v_lshl_add_u64 v[84:85], v[18:19], 2, v[10:11]
	global_load_dwordx4 v[100:103], v[84:85], off
	v_lshl_add_u64 v[86:87], v[20:21], 2, v[10:11]
	global_load_dwordx4 v[104:107], v[86:87], off
	v_lshl_add_u64 v[88:89], v[22:23], 2, v[10:11]
	global_load_dwordx4 v[108:111], v[88:89], off
	v_lshl_add_u64 v[90:91], v[24:25], 2, v[10:11]
	global_load_dwordx4 v[112:115], v[90:91], off
	v_lshl_add_u64 v[92:93], v[26:27], 2, v[10:11]
	global_load_dwordx4 v[116:119], v[92:93], off
	v_lshl_add_u64 v[94:95], v[28:29], 2, v[10:11]
	global_load_dwordx4 v[120:123], v[94:95], off
	v_lshl_add_u64 v[96:97], v[30:31], 2, v[10:11]
	global_load_dwordx4 v[124:127], v[96:97], off
	v_lshl_add_u64 v[98:99], v[32:33], 2, v[10:11]
	global_load_dwordx4 v[128:131], v[98:99], off
	s_lshl_b32 s36, s6, 1
	v_add_u32_e32 v48, s42, v52
	v_ashrrev_i32_e32 v49, 31, v48
	v_or_b32_e32 v82, s6, v53
	v_lshlrev_b64 v[48:49], 12, v[48:49]
	v_lshl_add_u64 v[48:49], s[76:77], 0, v[48:49]
	v_mov_b32_e32 v83, v0
	v_or_b32_e32 v2, s42, v51
	v_ashrrev_i32_e32 v3, 31, v2
	v_lshlrev_b64 v[2:3], 12, v[2:3]
	v_lshl_add_u64 v[2:3], s[76:77], 0, v[2:3]
	v_lshl_add_u64 v[6:7], v[2:3], 0, s[36:37]
	v_lshl_add_u64 v[132:133], v[34:35], 1, v[6:7]
	global_load_dwordx4 v[140:143], v[132:133], off offset:2048
	v_lshl_add_u64 v[134:135], v[36:37], 1, v[6:7]
	global_load_dwordx4 v[144:147], v[134:135], off offset:2048
	v_lshl_add_u64 v[136:137], v[38:39], 1, v[6:7]
	global_load_dwordx4 v[148:151], v[136:137], off offset:2048
	v_lshl_add_u64 v[138:139], v[40:41], 1, v[6:7]
	global_load_dwordx4 v[152:155], v[138:139], off offset:2048
	s_lshl_b32 s36, s7, 2
	v_lshl_add_u64 v[72:73], v[44:45], 0, s[36:37]
	global_load_dword v46, v[72:73], off
	v_lshlrev_b32_e32 v72, 2, v82
	v_lshlrev_b32_e32 v82, 1, v82
	v_lshl_add_u64 v[48:49], v[48:49], 0, v[82:83]
	global_load_dwordx4 v[180:183], v72, s[14:15]
	global_load_dwordx2 v[156:157], v[48:49], off
	global_load_dwordx4 v[184:187], v72, s[14:15] offset:64
	global_load_dwordx2 v[158:159], v[48:49], off offset:32
	global_load_dwordx4 v[188:191], v72, s[14:15] offset:128
	global_load_dwordx2 v[160:161], v[48:49], off offset:64
	global_load_dwordx4 v[192:195], v72, s[14:15] offset:192
	global_load_dwordx2 v[162:163], v[48:49], off offset:96
	global_load_dwordx4 v[196:199], v72, s[14:15] offset:256
	global_load_dwordx2 v[164:165], v[48:49], off offset:128
	global_load_dwordx4 v[200:203], v72, s[14:15] offset:320
	global_load_dwordx2 v[166:167], v[48:49], off offset:160
	global_load_dwordx4 v[204:207], v72, s[14:15] offset:384
	global_load_dwordx2 v[168:169], v[48:49], off offset:192
	global_load_dwordx4 v[208:211], v72, s[14:15] offset:448
	global_load_dwordx2 v[170:171], v[48:49], off offset:224
	v_readlane_b32 s6, v254, 42
	s_add_i32 s23, s23, s34
	s_add_i32 s22, s22, s92
	s_add_i32 s21, s21, s6
	s_cmpk_lt_i32 s23, 0x800
	s_waitcnt lgkmcnt(0)
	s_barrier
	ds_read_b128 v[6:9], v50
	s_waitcnt vmcnt(21) lgkmcnt(0)
	v_pk_mul_f32 v[102:103], v[102:103], v[8:9]
	v_pk_mul_f32 v[100:101], v[100:101], v[6:7]
	v_pk_mul_f32 v[106:107], v[106:107], v[8:9]
	v_pk_mul_f32 v[104:105], v[104:105], v[6:7]
	v_pk_mul_f32 v[110:111], v[110:111], v[8:9]
	v_pk_mul_f32 v[108:109], v[108:109], v[6:7]
	v_pk_mul_f32 v[114:115], v[114:115], v[8:9]
	v_pk_mul_f32 v[112:113], v[112:113], v[6:7]
	v_pk_mul_f32 v[118:119], v[118:119], v[8:9]
	v_pk_mul_f32 v[116:117], v[116:117], v[6:7]
	v_pk_mul_f32 v[122:123], v[122:123], v[8:9]
	v_pk_mul_f32 v[120:121], v[120:121], v[6:7]
	v_pk_mul_f32 v[126:127], v[126:127], v[8:9]
	v_pk_mul_f32 v[124:125], v[124:125], v[6:7]
	v_pk_mul_f32 v[130:131], v[130:131], v[8:9]
	v_pk_mul_f32 v[128:129], v[128:129], v[6:7]
	v_cvt_pk_bf16_f32 v100, v100, v101
	v_cvt_pk_bf16_f32 v101, v102, v103
	v_cvt_pk_bf16_f32 v104, v104, v105
	v_cvt_pk_bf16_f32 v105, v106, v107
	v_cvt_pk_bf16_f32 v108, v108, v109
	v_cvt_pk_bf16_f32 v109, v110, v111
	v_cvt_pk_bf16_f32 v112, v112, v113
	v_cvt_pk_bf16_f32 v113, v114, v115
	v_cvt_pk_bf16_f32 v116, v116, v117
	v_cvt_pk_bf16_f32 v117, v118, v119
	v_cvt_pk_bf16_f32 v120, v120, v121
	v_cvt_pk_bf16_f32 v121, v122, v123
	v_cvt_pk_bf16_f32 v124, v124, v125
	v_cvt_pk_bf16_f32 v125, v126, v127
	v_cvt_pk_bf16_f32 v128, v128, v129
	v_cvt_pk_bf16_f32 v129, v130, v131
	ds_write_b64 v54, v[100:101]
	ds_write_b64 v55, v[104:105]
	ds_write_b64 v56, v[108:109]
	ds_write_b64 v57, v[112:113]
	ds_write_b64 v58, v[116:117]
	ds_write_b64 v59, v[120:121]
	ds_write_b64 v60, v[124:125]
	ds_write_b64 v61, v[128:129]
	s_waitcnt vmcnt(17)
	ds_write_b16 v62, v140 offset:34816
	ds_write_b16_d16_hi v62, v140 offset:35088
	ds_write_b16 v62, v141 offset:35360
	ds_write_b16_d16_hi v62, v141 offset:35632
	ds_write_b16 v62, v142 offset:35904
	ds_write_b16_d16_hi v62, v142 offset:36176
	ds_write_b16 v62, v143 offset:36448
	ds_write_b16_d16_hi v63, v143 offset:34816
	ds_write_b16 v64, v144 offset:34816
	ds_write_b16_d16_hi v64, v144 offset:35088
	ds_write_b16 v64, v145 offset:35360
	ds_write_b16_d16_hi v64, v145 offset:35632
	ds_write_b16 v64, v146 offset:35904
	ds_write_b16_d16_hi v64, v146 offset:36176
	ds_write_b16 v64, v147 offset:36448
	ds_write_b16_d16_hi v65, v147 offset:34816
	ds_write_b16 v66, v148 offset:34816
	ds_write_b16_d16_hi v66, v148 offset:35088
	ds_write_b16 v66, v149 offset:35360
	ds_write_b16_d16_hi v66, v149 offset:35632
	ds_write_b16 v66, v150 offset:35904
	ds_write_b16_d16_hi v66, v150 offset:36176
	ds_write_b16 v66, v151 offset:36448
	ds_write_b16_d16_hi v67, v151 offset:34816
	ds_write_b16 v68, v152 offset:34816
	ds_write_b16_d16_hi v68, v152 offset:35088
	ds_write_b16 v68, v153 offset:35360
	ds_write_b16_d16_hi v68, v153 offset:35632
	ds_write_b16 v68, v154 offset:35904
	ds_write_b16_d16_hi v68, v154 offset:36176
	ds_write_b16 v68, v155 offset:36448
	ds_write_b16_d16_hi v69, v155 offset:34816
	s_waitcnt lgkmcnt(0)
	s_barrier
; __device__ __forceinline__ unsigned cvt_pk_bf16(float lo, float hi) { const f2_t v = {lo, hi}; const bf2_t b = __builtin_convertvector(v, bf2_t); return __builtin_bit_cast(unsigned, b); }
; __device__ __forceinline__ f32x4 mfma16(bf16x8 a, bf16x8 b, f32x4 c) { return __builtin_amdgcn_mfma_f32_16x16x32_bf16(a, b, c, 0, 0, 0); }
; __device__ void sg_phase(int wv, const Params& p, int jl, unsigned char* lds) {
;     ...
;         bf16x8 af[4];
; #pragma unroll
;         for (int kk = 0; kk < 4; ++kk) af[kk] = *(const bf16x8*)(WsL + (16 * w + lr) * PW + 32 * kk + 8 * lq);
;         const int tok = t0 + 16 * w + lr; const float bs = p.a_b_s[((size_t)jl * 8 + g) * 128 + 16 * w + lr];
; #pragma unroll
;         for (int db = 0; db < 8; ++db) { f32x4 acc = {0, 0, 0, 0};
; #pragma unroll
;             for (int kk = 0; kk < 4; ++kk) { const bf16x8 bf = *(const bf16x8*)(VTL + (16 * db + lr) * PW + 32 * kk + 8 * lq); acc = mfma16(bf, af[kk], acc); }
;             const int col = g * 128 + 16 * db + 4 * lq; const f32x4 gv = *(const f32x4*)(p.a_g_v + jl * DM + col);
;             bf16_t* up = uv + (size_t)tok * 2048 + col; const u32x2 uu = *(const u32x2*)up;
;             const float u0 = __uint_as_float(uu.x << 16), u1 = __uint_as_float(uu.x & 0xffff0000u), u2 = __uint_as_float(uu.y << 16), u3 = __uint_as_float(uu.y & 0xffff0000u);
;             const f32x4 sv = acc * gv + bs; u32x2 o; o.x = cvt_pk_bf16(u0 * sv[0], u1 * sv[1]); o.y = cvt_pk_bf16(u2 * sv[2], u3 * sv[3]);
;             *(u32x2*)up = o; }
	ds_read_b128 v[14:17], v70
	ds_read_b128 v[10:13], v70 offset:64
	ds_read_b128 v[6:9], v70 offset:128
	ds_read_b128 v[2:5], v70 offset:192
	ds_read_b128 v[72:75], v71 offset:34816
	ds_read_b128 v[76:79], v71 offset:34880
	s_waitcnt lgkmcnt(1)
	v_mfma_f32_16x16x32_bf16 v[72:75], v[72:75], v[14:17], 0
	s_waitcnt lgkmcnt(0)
	v_mfma_f32_16x16x32_bf16 v[72:75], v[76:79], v[10:13], v[72:75]
	ds_read_b128 v[76:79], v71 offset:34944
	s_waitcnt lgkmcnt(0)
	v_mfma_f32_16x16x32_bf16 v[72:75], v[76:79], v[6:9], v[72:75]
	ds_read_b128 v[76:79], v71 offset:35008
	s_waitcnt lgkmcnt(0)
	v_mfma_f32_16x16x32_bf16 v[74:77], v[76:79], v[2:5], v[72:75]
	s_nop 4
	s_waitcnt vmcnt(14)
	s_nop 7
	v_pk_fma_f32 v[74:75], v[74:75], v[180:181], v[46:47] op_sel_hi:[1,1,0]
	v_lshlrev_b32_e32 v78, 16, v156
	v_and_b32_e32 v79, 0xffff0000, v156
	v_pk_fma_f32 v[76:77], v[76:77], v[182:183], v[46:47] op_sel_hi:[1,1,0]
	v_pk_mul_f32 v[74:75], v[74:75], v[78:79]
	v_lshlrev_b32_e32 v78, 16, v157
	v_and_b32_e32 v79, 0xffff0000, v157
	v_pk_mul_f32 v[76:77], v[76:77], v[78:79]
	v_cvt_pk_bf16_f32 v74, v74, v75
	v_cvt_pk_bf16_f32 v75, v76, v77
	global_store_dwordx2 v[48:49], v[74:75], off
	ds_read_b128 v[74:77], v71 offset:39168
	ds_read_b128 v[78:81], v71 offset:39232
	s_waitcnt lgkmcnt(1)
	v_mfma_f32_16x16x32_bf16 v[74:77], v[74:77], v[14:17], 0
	s_waitcnt lgkmcnt(0)
	v_mfma_f32_16x16x32_bf16 v[74:77], v[78:81], v[10:13], v[74:77]
	ds_read_b128 v[78:81], v71 offset:39296
	s_waitcnt lgkmcnt(0)
	v_mfma_f32_16x16x32_bf16 v[74:77], v[78:81], v[6:9], v[74:77]
	ds_read_b128 v[78:81], v71 offset:39360
	s_waitcnt lgkmcnt(0)
	v_mfma_f32_16x16x32_bf16 v[74:77], v[78:81], v[2:5], v[74:77]
	s_waitcnt vmcnt(13)
	s_nop 7
	s_nop 4
	v_pk_fma_f32 v[74:75], v[74:75], v[184:185], v[46:47] op_sel_hi:[1,1,0]
	v_lshlrev_b32_e32 v78, 16, v158
	v_and_b32_e32 v79, 0xffff0000, v158
	v_pk_fma_f32 v[76:77], v[76:77], v[186:187], v[46:47] op_sel_hi:[1,1,0]
	v_pk_mul_f32 v[74:75], v[74:75], v[78:79]
	v_lshlrev_b32_e32 v78, 16, v159
	v_and_b32_e32 v79, 0xffff0000, v159
	v_pk_mul_f32 v[76:77], v[76:77], v[78:79]
	v_cvt_pk_bf16_f32 v74, v74, v75
	v_cvt_pk_bf16_f32 v75, v76, v77
	global_store_dwordx2 v[48:49], v[74:75], off offset:32
	ds_read_b128 v[74:77], v71 offset:43520
	ds_read_b128 v[78:81], v71 offset:43584
	s_waitcnt lgkmcnt(1)
	v_mfma_f32_16x16x32_bf16 v[74:77], v[74:77], v[14:17], 0
	s_waitcnt lgkmcnt(0)
	v_mfma_f32_16x16x32_bf16 v[74:77], v[78:81], v[10:13], v[74:77]
	ds_read_b128 v[78:81], v71 offset:43648
	s_waitcnt lgkmcnt(0)
	v_mfma_f32_16x16x32_bf16 v[74:77], v[78:81], v[6:9], v[74:77]
	ds_read_b128 v[78:81], v71 offset:43712
	s_waitcnt lgkmcnt(0)
	v_mfma_f32_16x16x32_bf16 v[74:77], v[78:81], v[2:5], v[74:77]
	s_waitcnt vmcnt(12)
	s_nop 7
	s_nop 4
	v_pk_fma_f32 v[74:75], v[74:75], v[188:189], v[46:47] op_sel_hi:[1,1,0]
	v_lshlrev_b32_e32 v78, 16, v160
	v_and_b32_e32 v79, 0xffff0000, v160
	v_pk_fma_f32 v[76:77], v[76:77], v[190:191], v[46:47] op_sel_hi:[1,1,0]
	v_pk_mul_f32 v[74:75], v[74:75], v[78:79]
	v_lshlrev_b32_e32 v78, 16, v161
	v_and_b32_e32 v79, 0xffff0000, v161
	v_pk_mul_f32 v[76:77], v[76:77], v[78:79]
	v_cvt_pk_bf16_f32 v74, v74, v75
	v_cvt_pk_bf16_f32 v75, v76, v77
	global_store_dwordx2 v[48:49], v[74:75], off offset:64
	ds_read_b128 v[74:77], v71 offset:47872
	ds_read_b128 v[78:81], v71 offset:47936
	s_waitcnt lgkmcnt(1)
	v_mfma_f32_16x16x32_bf16 v[74:77], v[74:77], v[14:17], 0
	s_waitcnt lgkmcnt(0)
	v_mfma_f32_16x16x32_bf16 v[74:77], v[78:81], v[10:13], v[74:77]
	ds_read_b128 v[78:81], v71 offset:48000
	s_waitcnt lgkmcnt(0)
	v_mfma_f32_16x16x32_bf16 v[74:77], v[78:81], v[6:9], v[74:77]
	ds_read_b128 v[78:81], v71 offset:48064
	s_waitcnt lgkmcnt(0)
	v_mfma_f32_16x16x32_bf16 v[74:77], v[78:81], v[2:5], v[74:77]
	s_waitcnt vmcnt(11)
	s_nop 7
	s_nop 4
	v_pk_fma_f32 v[74:75], v[74:75], v[192:193], v[46:47] op_sel_hi:[1,1,0]
	v_lshlrev_b32_e32 v78, 16, v162
	v_and_b32_e32 v79, 0xffff0000, v162
	v_pk_fma_f32 v[76:77], v[76:77], v[194:195], v[46:47] op_sel_hi:[1,1,0]
	v_pk_mul_f32 v[74:75], v[74:75], v[78:79]
	v_lshlrev_b32_e32 v78, 16, v163
	v_and_b32_e32 v79, 0xffff0000, v163
	v_pk_mul_f32 v[76:77], v[76:77], v[78:79]
	v_cvt_pk_bf16_f32 v74, v74, v75
	v_cvt_pk_bf16_f32 v75, v76, v77
	global_store_dwordx2 v[48:49], v[74:75], off offset:96
	ds_read_b128 v[74:77], v71 offset:52224
	ds_read_b128 v[78:81], v71 offset:52288
	s_waitcnt lgkmcnt(1)
; __device__ __forceinline__ unsigned cvt_pk_bf16(float lo, float hi) { const f2_t v = {lo, hi}; const bf2_t b = __builtin_convertvector(v, bf2_t); return __builtin_bit_cast(unsigned, b); }
; __device__ __forceinline__ f32x4 mfma16(bf16x8 a, bf16x8 b, f32x4 c) { return __builtin_amdgcn_mfma_f32_16x16x32_bf16(a, b, c, 0, 0, 0); }
; __device__ void sg_phase(int wv, const Params& p, int jl, unsigned char* lds) {
;     ...
;         for (int db = 0; db < 8; ++db) { f32x4 acc = {0, 0, 0, 0};
; #pragma unroll
;             for (int kk = 0; kk < 4; ++kk) { const bf16x8 bf = *(const bf16x8*)(VTL + (16 * db + lr) * PW + 32 * kk + 8 * lq); acc = mfma16(bf, af[kk], acc); }
;             const int col = g * 128 + 16 * db + 4 * lq; const f32x4 gv = *(const f32x4*)(p.a_g_v + jl * DM + col);
;             bf16_t* up = uv + (size_t)tok * 2048 + col; const u32x2 uu = *(const u32x2*)up;
;             const float u0 = __uint_as_float(uu.x << 16), u1 = __uint_as_float(uu.x & 0xffff0000u), u2 = __uint_as_float(uu.y << 16), u3 = __uint_as_float(uu.y & 0xffff0000u);
;             const f32x4 sv = acc * gv + bs; u32x2 o; o.x = cvt_pk_bf16(u0 * sv[0], u1 * sv[1]); o.y = cvt_pk_bf16(u2 * sv[2], u3 * sv[3]);
;             *(u32x2*)up = o; }
;         __syncthreads();
	v_mfma_f32_16x16x32_bf16 v[74:77], v[74:77], v[14:17], 0
	s_waitcnt lgkmcnt(0)
	v_mfma_f32_16x16x32_bf16 v[74:77], v[78:81], v[10:13], v[74:77]
	ds_read_b128 v[78:81], v71 offset:52352
	s_waitcnt lgkmcnt(0)
	v_mfma_f32_16x16x32_bf16 v[74:77], v[78:81], v[6:9], v[74:77]
	ds_read_b128 v[78:81], v71 offset:52416
	s_waitcnt lgkmcnt(0)
	v_mfma_f32_16x16x32_bf16 v[74:77], v[78:81], v[2:5], v[74:77]
	s_waitcnt vmcnt(10)
	s_nop 7
	s_nop 4
	v_pk_fma_f32 v[74:75], v[74:75], v[196:197], v[46:47] op_sel_hi:[1,1,0]
	v_lshlrev_b32_e32 v78, 16, v164
	v_and_b32_e32 v79, 0xffff0000, v164
	v_pk_fma_f32 v[76:77], v[76:77], v[198:199], v[46:47] op_sel_hi:[1,1,0]
	v_pk_mul_f32 v[74:75], v[74:75], v[78:79]
	v_lshlrev_b32_e32 v78, 16, v165
	v_and_b32_e32 v79, 0xffff0000, v165
	v_pk_mul_f32 v[76:77], v[76:77], v[78:79]
	v_cvt_pk_bf16_f32 v74, v74, v75
	v_cvt_pk_bf16_f32 v75, v76, v77
	global_store_dwordx2 v[48:49], v[74:75], off offset:128
	ds_read_b128 v[74:77], v71 offset:56576
	ds_read_b128 v[78:81], v71 offset:56640
	s_waitcnt lgkmcnt(1)
	v_mfma_f32_16x16x32_bf16 v[74:77], v[74:77], v[14:17], 0
	s_waitcnt lgkmcnt(0)
	v_mfma_f32_16x16x32_bf16 v[74:77], v[78:81], v[10:13], v[74:77]
	ds_read_b128 v[78:81], v71 offset:56704
	s_waitcnt lgkmcnt(0)
	v_mfma_f32_16x16x32_bf16 v[74:77], v[78:81], v[6:9], v[74:77]
	ds_read_b128 v[78:81], v71 offset:56768
	s_waitcnt lgkmcnt(0)
	v_mfma_f32_16x16x32_bf16 v[74:77], v[78:81], v[2:5], v[74:77]
	s_waitcnt vmcnt(9)
	s_nop 7
	s_nop 4
	v_pk_fma_f32 v[74:75], v[74:75], v[200:201], v[46:47] op_sel_hi:[1,1,0]
	v_lshlrev_b32_e32 v78, 16, v166
	v_and_b32_e32 v79, 0xffff0000, v166
	v_pk_fma_f32 v[76:77], v[76:77], v[202:203], v[46:47] op_sel_hi:[1,1,0]
	v_pk_mul_f32 v[74:75], v[74:75], v[78:79]
	v_lshlrev_b32_e32 v78, 16, v167
	v_and_b32_e32 v79, 0xffff0000, v167
	v_pk_mul_f32 v[76:77], v[76:77], v[78:79]
	v_cvt_pk_bf16_f32 v74, v74, v75
	v_cvt_pk_bf16_f32 v75, v76, v77
	global_store_dwordx2 v[48:49], v[74:75], off offset:160
	ds_read_b128 v[74:77], v71 offset:60928
	ds_read_b128 v[78:81], v71 offset:60992
	s_waitcnt lgkmcnt(1)
	v_mfma_f32_16x16x32_bf16 v[74:77], v[74:77], v[14:17], 0
	s_waitcnt lgkmcnt(0)
	v_mfma_f32_16x16x32_bf16 v[74:77], v[78:81], v[10:13], v[74:77]
	ds_read_b128 v[78:81], v71 offset:61056
	s_waitcnt lgkmcnt(0)
	v_mfma_f32_16x16x32_bf16 v[74:77], v[78:81], v[6:9], v[74:77]
	ds_read_b128 v[78:81], v71 offset:61120
	s_waitcnt lgkmcnt(0)
	v_mfma_f32_16x16x32_bf16 v[74:77], v[78:81], v[2:5], v[74:77]
	s_waitcnt vmcnt(8)
	s_nop 7
	s_nop 4
	v_pk_fma_f32 v[74:75], v[74:75], v[204:205], v[46:47] op_sel_hi:[1,1,0]
	v_lshlrev_b32_e32 v78, 16, v168
	v_and_b32_e32 v79, 0xffff0000, v168
	v_pk_fma_f32 v[76:77], v[76:77], v[206:207], v[46:47] op_sel_hi:[1,1,0]
	v_pk_mul_f32 v[74:75], v[74:75], v[78:79]
	v_lshlrev_b32_e32 v78, 16, v169
	v_and_b32_e32 v79, 0xffff0000, v169
	v_pk_mul_f32 v[76:77], v[76:77], v[78:79]
	v_cvt_pk_bf16_f32 v74, v74, v75
	v_cvt_pk_bf16_f32 v75, v76, v77
	global_store_dwordx2 v[48:49], v[74:75], off offset:192
	ds_read_b128 v[74:77], v71 offset:65280
	s_waitcnt lgkmcnt(0)
	v_mfma_f32_16x16x32_bf16 v[14:17], v[74:77], v[14:17], 0
	ds_read_b128 v[74:77], v71 offset:65344
	s_waitcnt lgkmcnt(0)
	v_mfma_f32_16x16x32_bf16 v[10:13], v[74:77], v[10:13], v[14:17]
	s_nop 4
	ds_read_b128 v[14:17], v71 offset:65408
	s_waitcnt lgkmcnt(0)
	v_mfma_f32_16x16x32_bf16 v[6:9], v[14:17], v[6:9], v[10:13]
	s_nop 2
	ds_read_b128 v[10:13], v71 offset:65472
	s_waitcnt lgkmcnt(0)
	v_mfma_f32_16x16x32_bf16 v[2:5], v[10:13], v[2:5], v[6:9]
	s_nop 2
	s_waitcnt vmcnt(7)
	s_nop 7
	s_nop 1
	v_pk_fma_f32 v[2:3], v[2:3], v[208:209], v[46:47] op_sel_hi:[1,1,0]
	v_lshlrev_b32_e32 v6, 16, v170
	v_and_b32_e32 v7, 0xffff0000, v170
	v_pk_fma_f32 v[4:5], v[4:5], v[210:211], v[46:47] op_sel_hi:[1,1,0]
	v_pk_mul_f32 v[2:3], v[2:3], v[6:7]
	v_lshlrev_b32_e32 v6, 16, v171
	v_and_b32_e32 v7, 0xffff0000, v171
	v_pk_mul_f32 v[4:5], v[4:5], v[6:7]
	v_cvt_pk_bf16_f32 v2, v2, v3
	v_cvt_pk_bf16_f32 v3, v4, v5
	global_store_dwordx2 v[48:49], v[2:3], off offset:224
	s_barrier
	s_cbranch_scc0 .LBB0_290

; __device__ __forceinline__ unsigned cvt_pk_bf16_asm(float lo, float hi) { unsigned r; asm volatile("v_cvt_pk_bf16_f32 %0, %1, %2" : "=v"(r) : "v"(lo), "v"(hi)); return r; }
;     __device__ __forceinline__ void operator()(const f32x4 (&acc)[2][2][4][2], const Unit& u, int wr, int wc, int fr, int fq) const {
;     ...
; #pragma unroll
;         for (int g8 = 0; g8 < 8; ++g8) { const int ai = g8 >> 2, m = g8 & 3;
;             ERES_LOAD(0, g8);
;             const int r = row0 + ai * HALF + m * 16; float s = 0.f;
; #pragma unroll
;             for (int bj = 0; bj < 2; ++bj) { const f32x4 x0 = xr[0][bj][0] + gv[bj][0] * acc[ai][bj][m][0], x1 = xr[0][bj][1] + gv[bj][1] * acc[ai][bj][m][1];
;                 s += (x0[0] * x0[0] + x0[1] * x0[1]) + (x0[2] * x0[2] + x0[3] * x0[3]) + (x1[0] * x1[0] + x1[1] * x1[1]) + (x1[2] * x1[2] + x1[3] * x1[3]);
;                 u32x4 w; w.x = cvt_pk_bf16_asm(x0[0], x0[1]); w.y = cvt_pk_bf16_asm(x0[2], x0[3]); w.z = cvt_pk_bf16_asm(x1[0], x1[1]); w.w = cvt_pk_bf16_asm(x1[2], x1[3]);
;                 *(u32x4*)(xh + (size_t)r * DM + col0 + bj * HALF) = w;
;                 if (xb) { const f32x4 h0 = x0 * gsv[bj][0], h1 = x1 * gsv[bj][1]; u32x4 wb; wb.x = cvt_pk_bf16_asm(h0[0], h0[1]); wb.y = cvt_pk_bf16_asm(h0[2], h0[3]); wb.z = cvt_pk_bf16_asm(h1[0], h1[1]); wb.w = cvt_pk_bf16_asm(h1[2], h1[3]);
;                     *(u32x4*)(xb + (size_t)r * DM + col0 + bj * HALF) = wb; } }
.Lres_bf16:
	v_lshlrev_b32_e32 v195, 11, v194
	v_lshl_add_u32 v195, v192, 1, v195
	v_lshlrev_b32_e32 v193, 3, v194
	s_mov_b64 s[8:9], s[28:29]
	global_load_dwordx4 v[162:165], v195, s[8:9]
	global_load_dwordx4 v[166:169], v195, s[8:9] offset:256
	s_add_u32 s8, s28, 0x8000
	s_addc_u32 s9, s29, 0
	global_load_dwordx4 v[196:199], v195, s[8:9]
	global_load_dwordx4 v[202:205], v195, s[8:9] offset:256
	s_and_b64 vcc, exec, s[52:53]
	s_waitcnt vmcnt(2)
	v_lshlrev_b32_e32 v170, 16, v162
	v_and_b32_e32 v171, 0xffff0000, v162
	v_pk_fma_f32 v[158:159], v[78:79], v[158:159], v[170:171]
	v_lshlrev_b32_e32 v172, 16, v163
	v_and_b32_e32 v173, 0xffff0000, v163
	v_pk_fma_f32 v[160:161], v[80:81], v[160:161], v[172:173]
	v_lshlrev_b32_e32 v174, 16, v164
	v_and_b32_e32 v175, 0xffff0000, v164
	v_pk_fma_f32 v[154:155], v[74:75], v[154:155], v[174:175]
	v_lshlrev_b32_e32 v176, 16, v165
	v_and_b32_e32 v177, 0xffff0000, v165
	v_pk_fma_f32 v[156:157], v[76:77], v[156:157], v[176:177]
	v_lshlrev_b32_e32 v170, 16, v166
	v_and_b32_e32 v171, 0xffff0000, v166
	v_pk_fma_f32 v[150:151], v[62:63], v[150:151], v[170:171]
	v_lshlrev_b32_e32 v172, 16, v167
	v_and_b32_e32 v173, 0xffff0000, v167
	v_pk_fma_f32 v[152:153], v[64:65], v[152:153], v[172:173]
	v_lshlrev_b32_e32 v174, 16, v168
	v_and_b32_e32 v175, 0xffff0000, v168
	v_pk_fma_f32 v[146:147], v[58:59], v[146:147], v[174:175]
	v_lshlrev_b32_e32 v176, 16, v169
	v_and_b32_e32 v177, 0xffff0000, v169
	v_pk_fma_f32 v[148:149], v[60:61], v[148:149], v[176:177]
	v_cvt_pk_bf16_f32 v170, v158, v159
	v_cvt_pk_bf16_f32 v171, v160, v161
	v_cvt_pk_bf16_f32 v172, v154, v155
	v_cvt_pk_bf16_f32 v173, v156, v157
	v_cvt_pk_bf16_f32 v174, v150, v151
	v_cvt_pk_bf16_f32 v175, v152, v153
	v_cvt_pk_bf16_f32 v176, v146, v147
	v_cvt_pk_bf16_f32 v177, v148, v149
	s_mov_b64 s[8:9], s[28:29]
	global_store_dwordx4 v195, v[170:173], s[8:9]
	global_store_dwordx4 v195, v[174:177], s[8:9] offset:256
	v_mul_f32_e32 v192, v158, v158
	v_mul_f32_e32 v162, v159, v159
	v_fmac_f32_e32 v192, v160, v160
	v_fmac_f32_e32 v162, v161, v161
	v_fmac_f32_e32 v192, v154, v154
	v_fmac_f32_e32 v162, v155, v155
	v_fmac_f32_e32 v192, v156, v156
	v_fmac_f32_e32 v162, v157, v157
	v_fmac_f32_e32 v192, v150, v150
	v_fmac_f32_e32 v162, v151, v151
	v_fmac_f32_e32 v192, v152, v152
	v_fmac_f32_e32 v162, v153, v153
	v_fmac_f32_e32 v192, v146, v146
	v_fmac_f32_e32 v162, v147, v147
	v_fmac_f32_e32 v192, v148, v148
	v_fmac_f32_e32 v162, v149, v149
	v_add_f32_e32 v192, v192, v162
	s_cbranch_vccz .Lres_noxb_0
	v_pk_mul_f32 v[158:159], v[158:159], v[70:71]
	v_pk_mul_f32 v[160:161], v[160:161], v[72:73]
	v_pk_mul_f32 v[154:155], v[154:155], v[66:67]
	v_pk_mul_f32 v[156:157], v[156:157], v[68:69]
	v_pk_mul_f32 v[150:151], v[150:151], v[54:55]
	v_pk_mul_f32 v[152:153], v[152:153], v[56:57]
	v_pk_mul_f32 v[146:147], v[146:147], v[50:51]
	v_pk_mul_f32 v[148:149], v[148:149], v[52:53]
	v_cvt_pk_bf16_f32 v162, v158, v159
	v_cvt_pk_bf16_f32 v163, v160, v161
	v_cvt_pk_bf16_f32 v164, v154, v155
	v_cvt_pk_bf16_f32 v165, v156, v157
	v_cvt_pk_bf16_f32 v166, v150, v151
	v_cvt_pk_bf16_f32 v167, v152, v153
	v_cvt_pk_bf16_f32 v168, v146, v147
	v_cvt_pk_bf16_f32 v169, v148, v149
	s_mov_b64 s[4:5], s[62:63]
	global_store_dwordx4 v195, v[162:165], s[4:5]
	global_store_dwordx4 v195, v[166:169], s[4:5] offset:256
.Lres_noxb_0:
	s_add_u32 s8, s28, 0x10000
	s_addc_u32 s9, s29, 0
	global_load_dwordx4 v[158:161], v195, s[8:9]
	global_load_dwordx4 v[154:157], v195, s[8:9] offset:256
	s_add_u32 s8, s28, 0x18000
	s_addc_u32 s9, s29, 0
	global_load_dwordx4 v[150:153], v195, s[8:9]
	global_load_dwordx4 v[146:149], v195, s[8:9] offset:256
	s_waitcnt vmcnt(6)
	v_lshlrev_b32_e32 v170, 16, v196
	v_and_b32_e32 v171, 0xffff0000, v196
	v_pk_fma_f32 v[142:143], v[78:79], v[142:143], v[170:171]
	v_lshlrev_b32_e32 v172, 16, v197
	v_and_b32_e32 v173, 0xffff0000, v197
	v_pk_fma_f32 v[144:145], v[80:81], v[144:145], v[172:173]
	v_lshlrev_b32_e32 v174, 16, v198
	v_and_b32_e32 v175, 0xffff0000, v198
	v_pk_fma_f32 v[138:139], v[74:75], v[138:139], v[174:175]
	v_lshlrev_b32_e32 v176, 16, v199
	v_and_b32_e32 v177, 0xffff0000, v199
	v_pk_fma_f32 v[140:141], v[76:77], v[140:141], v[176:177]
	v_lshlrev_b32_e32 v170, 16, v202
	v_and_b32_e32 v171, 0xffff0000, v202
	v_pk_fma_f32 v[134:135], v[62:63], v[134:135], v[170:171]
	v_lshlrev_b32_e32 v172, 16, v203
	v_and_b32_e32 v173, 0xffff0000, v203
	v_pk_fma_f32 v[136:137], v[64:65], v[136:137], v[172:173]
	v_lshlrev_b32_e32 v174, 16, v204
	v_and_b32_e32 v175, 0xffff0000, v204
	v_pk_fma_f32 v[130:131], v[58:59], v[130:131], v[174:175]
	v_lshlrev_b32_e32 v176, 16, v205
	v_and_b32_e32 v177, 0xffff0000, v205
	v_pk_fma_f32 v[132:133], v[60:61], v[132:133], v[176:177]
	v_cvt_pk_bf16_f32 v170, v142, v143
	v_cvt_pk_bf16_f32 v171, v144, v145
	v_cvt_pk_bf16_f32 v172, v138, v139
	v_cvt_pk_bf16_f32 v173, v140, v141
	v_cvt_pk_bf16_f32 v174, v134, v135
	v_cvt_pk_bf16_f32 v175, v136, v137
	v_cvt_pk_bf16_f32 v176, v130, v131
	v_cvt_pk_bf16_f32 v177, v132, v133
	s_add_u32 s8, s28, 0x8000
	s_addc_u32 s9, s29, 0
	global_store_dwordx4 v195, v[170:173], s[8:9]
	global_store_dwordx4 v195, v[174:177], s[8:9] offset:256
	v_mul_f32_e32 v194, v142, v142
	v_mul_f32_e32 v196, v143, v143
	v_fmac_f32_e32 v194, v144, v144
	v_fmac_f32_e32 v196, v145, v145
	v_fmac_f32_e32 v194, v138, v138
	v_fmac_f32_e32 v196, v139, v139
	v_fmac_f32_e32 v194, v140, v140
	v_fmac_f32_e32 v196, v141, v141
	v_fmac_f32_e32 v194, v134, v134
	v_fmac_f32_e32 v196, v135, v135
	v_fmac_f32_e32 v194, v136, v136
	v_fmac_f32_e32 v196, v137, v137
	v_fmac_f32_e32 v194, v130, v130
	v_fmac_f32_e32 v196, v131, v131
	v_fmac_f32_e32 v194, v132, v132
	v_fmac_f32_e32 v196, v133, v133
	v_add_f32_e32 v194, v194, v196
	s_cbranch_vccz .Lres_noxb_1
	v_pk_mul_f32 v[142:143], v[142:143], v[70:71]
	v_pk_mul_f32 v[144:145], v[144:145], v[72:73]
	v_pk_mul_f32 v[138:139], v[138:139], v[66:67]
	v_pk_mul_f32 v[140:141], v[140:141], v[68:69]
	v_pk_mul_f32 v[134:135], v[134:135], v[54:55]
	v_pk_mul_f32 v[136:137], v[136:137], v[56:57]
	v_pk_mul_f32 v[130:131], v[130:131], v[50:51]
	v_pk_mul_f32 v[132:133], v[132:133], v[52:53]
	v_cvt_pk_bf16_f32 v196, v142, v143
	v_cvt_pk_bf16_f32 v197, v144, v145
	v_cvt_pk_bf16_f32 v198, v138, v139
	v_cvt_pk_bf16_f32 v199, v140, v141
	v_cvt_pk_bf16_f32 v202, v134, v135
	v_cvt_pk_bf16_f32 v203, v136, v137
	v_cvt_pk_bf16_f32 v204, v130, v131
	v_cvt_pk_bf16_f32 v205, v132, v133
	s_add_u32 s4, s62, 0x8000
	s_addc_u32 s5, s63, 0
	global_store_dwordx4 v195, v[196:199], s[4:5]
	global_store_dwordx4 v195, v[202:205], s[4:5] offset:256
; __device__ __forceinline__ unsigned cvt_pk_bf16_asm(float lo, float hi) { unsigned r; asm volatile("v_cvt_pk_bf16_f32 %0, %1, %2" : "=v"(r) : "v"(lo), "v"(hi)); return r; }
;     __device__ __forceinline__ void operator()(const f32x4 (&acc)[2][2][4][2], const Unit& u, int wr, int wc, int fr, int fq) const {
;     ...
;         for (int g8 = 0; g8 < 8; ++g8) { const int ai = g8 >> 2, m = g8 & 3;
;             ERES_LOAD(0, g8);
;             const int r = row0 + ai * HALF + m * 16; float s = 0.f;
; #pragma unroll
;             for (int bj = 0; bj < 2; ++bj) { const f32x4 x0 = xr[0][bj][0] + gv[bj][0] * acc[ai][bj][m][0], x1 = xr[0][bj][1] + gv[bj][1] * acc[ai][bj][m][1];
;                 s += (x0[0] * x0[0] + x0[1] * x0[1]) + (x0[2] * x0[2] + x0[3] * x0[3]) + (x1[0] * x1[0] + x1[1] * x1[1]) + (x1[2] * x1[2] + x1[3] * x1[3]);
;                 u32x4 w; w.x = cvt_pk_bf16_asm(x0[0], x0[1]); w.y = cvt_pk_bf16_asm(x0[2], x0[3]); w.z = cvt_pk_bf16_asm(x1[0], x1[1]); w.w = cvt_pk_bf16_asm(x1[2], x1[3]);
;                 *(u32x4*)(xh + (size_t)r * DM + col0 + bj * HALF) = w;
;                 if (xb) { const f32x4 h0 = x0 * gsv[bj][0], h1 = x1 * gsv[bj][1]; u32x4 wb; wb.x = cvt_pk_bf16_asm(h0[0], h0[1]); wb.y = cvt_pk_bf16_asm(h0[2], h0[3]); wb.z = cvt_pk_bf16_asm(h1[0], h1[1]); wb.w = cvt_pk_bf16_asm(h1[2], h1[3]);
;                     *(u32x4*)(xb + (size_t)r * DM + col0 + bj * HALF) = wb; } }
.Lres_noxb_1:
	s_add_u32 s8, s28, 0x40000
	s_addc_u32 s9, s29, 0
	global_load_dwordx4 v[142:145], v195, s[8:9]
	global_load_dwordx4 v[138:141], v195, s[8:9] offset:256
	s_add_u32 s8, s28, 0x48000
	s_addc_u32 s9, s29, 0
	global_load_dwordx4 v[134:137], v195, s[8:9]
	global_load_dwordx4 v[130:133], v195, s[8:9] offset:256
	s_waitcnt vmcnt(8)
	v_lshlrev_b32_e32 v170, 16, v158
	v_and_b32_e32 v171, 0xffff0000, v158
	v_pk_fma_f32 v[126:127], v[78:79], v[126:127], v[170:171]
	v_lshlrev_b32_e32 v172, 16, v159
	v_and_b32_e32 v173, 0xffff0000, v159
	v_pk_fma_f32 v[128:129], v[80:81], v[128:129], v[172:173]
	v_lshlrev_b32_e32 v174, 16, v160
	v_and_b32_e32 v175, 0xffff0000, v160
	v_pk_fma_f32 v[122:123], v[74:75], v[122:123], v[174:175]
	v_lshlrev_b32_e32 v176, 16, v161
	v_and_b32_e32 v177, 0xffff0000, v161
	v_pk_fma_f32 v[124:125], v[76:77], v[124:125], v[176:177]
	v_lshlrev_b32_e32 v170, 16, v154
	v_and_b32_e32 v171, 0xffff0000, v154
	v_pk_fma_f32 v[118:119], v[62:63], v[118:119], v[170:171]
	v_lshlrev_b32_e32 v172, 16, v155
	v_and_b32_e32 v173, 0xffff0000, v155
	v_pk_fma_f32 v[120:121], v[64:65], v[120:121], v[172:173]
	v_lshlrev_b32_e32 v174, 16, v156
	v_and_b32_e32 v175, 0xffff0000, v156
	v_pk_fma_f32 v[114:115], v[58:59], v[114:115], v[174:175]
	v_lshlrev_b32_e32 v176, 16, v157
	v_and_b32_e32 v177, 0xffff0000, v157
	v_pk_fma_f32 v[116:117], v[60:61], v[116:117], v[176:177]
	v_cvt_pk_bf16_f32 v170, v126, v127
	v_cvt_pk_bf16_f32 v171, v128, v129
	v_cvt_pk_bf16_f32 v172, v122, v123
	v_cvt_pk_bf16_f32 v173, v124, v125
	v_cvt_pk_bf16_f32 v174, v118, v119
	v_cvt_pk_bf16_f32 v175, v120, v121
	v_cvt_pk_bf16_f32 v176, v114, v115
	v_cvt_pk_bf16_f32 v177, v116, v117
	s_add_u32 s8, s28, 0x10000
	s_addc_u32 s9, s29, 0
	global_store_dwordx4 v195, v[170:173], s[8:9]
	global_store_dwordx4 v195, v[174:177], s[8:9] offset:256
	v_mul_f32_e32 v196, v126, v126
	v_mul_f32_e32 v158, v127, v127
	v_fmac_f32_e32 v196, v128, v128
	v_fmac_f32_e32 v158, v129, v129
	v_fmac_f32_e32 v196, v122, v122
	v_fmac_f32_e32 v158, v123, v123
	v_fmac_f32_e32 v196, v124, v124
	v_fmac_f32_e32 v158, v125, v125
	v_fmac_f32_e32 v196, v118, v118
	v_fmac_f32_e32 v158, v119, v119
	v_fmac_f32_e32 v196, v120, v120
	v_fmac_f32_e32 v158, v121, v121
	v_fmac_f32_e32 v196, v114, v114
	v_fmac_f32_e32 v158, v115, v115
	v_fmac_f32_e32 v196, v116, v116
	v_fmac_f32_e32 v158, v117, v117
	v_add_f32_e32 v196, v196, v158
	s_cbranch_vccz .Lres_noxb_2
	v_pk_mul_f32 v[126:127], v[126:127], v[70:71]
	v_pk_mul_f32 v[128:129], v[128:129], v[72:73]
	v_pk_mul_f32 v[122:123], v[122:123], v[66:67]
	v_pk_mul_f32 v[124:125], v[124:125], v[68:69]
	v_pk_mul_f32 v[118:119], v[118:119], v[54:55]
	v_pk_mul_f32 v[120:121], v[120:121], v[56:57]
	v_pk_mul_f32 v[114:115], v[114:115], v[50:51]
	v_pk_mul_f32 v[116:117], v[116:117], v[52:53]
	v_cvt_pk_bf16_f32 v158, v126, v127
	v_cvt_pk_bf16_f32 v159, v128, v129
	v_cvt_pk_bf16_f32 v160, v122, v123
	v_cvt_pk_bf16_f32 v161, v124, v125
	v_cvt_pk_bf16_f32 v154, v118, v119
	v_cvt_pk_bf16_f32 v155, v120, v121
	v_cvt_pk_bf16_f32 v156, v114, v115
	v_cvt_pk_bf16_f32 v157, v116, v117
	s_add_u32 s4, s62, 0x10000
	s_addc_u32 s5, s63, 0
	global_store_dwordx4 v195, v[158:161], s[4:5]
	global_store_dwordx4 v195, v[154:157], s[4:5] offset:256
.Lres_noxb_2:
	s_add_u32 s8, s28, 0x50000
	s_addc_u32 s9, s29, 0
	global_load_dwordx4 v[126:129], v195, s[8:9]
	global_load_dwordx4 v[122:125], v195, s[8:9] offset:256
	s_add_u32 s8, s28, 0x58000
	s_addc_u32 s9, s29, 0
	global_load_dwordx4 v[118:121], v195, s[8:9]
	global_load_dwordx4 v[114:117], v195, s[8:9] offset:256
	s_waitcnt vmcnt(12)
	v_lshlrev_b32_e32 v170, 16, v150
	v_and_b32_e32 v171, 0xffff0000, v150
	v_pk_fma_f32 v[110:111], v[78:79], v[110:111], v[170:171]
	v_lshlrev_b32_e32 v172, 16, v151
	v_and_b32_e32 v173, 0xffff0000, v151
	v_pk_fma_f32 v[112:113], v[80:81], v[112:113], v[172:173]
	v_lshlrev_b32_e32 v174, 16, v152
	v_and_b32_e32 v175, 0xffff0000, v152
	v_pk_fma_f32 v[106:107], v[74:75], v[106:107], v[174:175]
	v_lshlrev_b32_e32 v176, 16, v153
	v_and_b32_e32 v177, 0xffff0000, v153
	v_pk_fma_f32 v[108:109], v[76:77], v[108:109], v[176:177]
	v_lshlrev_b32_e32 v170, 16, v146
	v_and_b32_e32 v171, 0xffff0000, v146
	v_pk_fma_f32 v[102:103], v[62:63], v[102:103], v[170:171]
	v_lshlrev_b32_e32 v172, 16, v147
	v_and_b32_e32 v173, 0xffff0000, v147
	v_pk_fma_f32 v[104:105], v[64:65], v[104:105], v[172:173]
	v_lshlrev_b32_e32 v174, 16, v148
	v_and_b32_e32 v175, 0xffff0000, v148
	v_pk_fma_f32 v[98:99], v[58:59], v[98:99], v[174:175]
	v_lshlrev_b32_e32 v176, 16, v149
	v_and_b32_e32 v177, 0xffff0000, v149
	v_pk_fma_f32 v[100:101], v[60:61], v[100:101], v[176:177]
	v_cvt_pk_bf16_f32 v170, v110, v111
	v_cvt_pk_bf16_f32 v171, v112, v113
	v_cvt_pk_bf16_f32 v172, v106, v107
	v_cvt_pk_bf16_f32 v173, v108, v109
	v_cvt_pk_bf16_f32 v174, v102, v103
	v_cvt_pk_bf16_f32 v175, v104, v105
	v_cvt_pk_bf16_f32 v176, v98, v99
	v_cvt_pk_bf16_f32 v177, v100, v101
	s_add_u32 s8, s28, 0x18000
	s_addc_u32 s9, s29, 0
	global_store_dwordx4 v195, v[170:173], s[8:9]
	global_store_dwordx4 v195, v[174:177], s[8:9] offset:256
	v_mul_f32_e32 v197, v110, v110
	v_mul_f32_e32 v150, v111, v111
	v_fmac_f32_e32 v197, v112, v112
	v_fmac_f32_e32 v150, v113, v113
	v_fmac_f32_e32 v197, v106, v106
	v_fmac_f32_e32 v150, v107, v107
	v_fmac_f32_e32 v197, v108, v108
	v_fmac_f32_e32 v150, v109, v109
	v_fmac_f32_e32 v197, v102, v102
	v_fmac_f32_e32 v150, v103, v103
	v_fmac_f32_e32 v197, v104, v104
	v_fmac_f32_e32 v150, v105, v105
	v_fmac_f32_e32 v197, v98, v98
	v_fmac_f32_e32 v150, v99, v99
	v_fmac_f32_e32 v197, v100, v100
	v_fmac_f32_e32 v150, v101, v101
	v_add_f32_e32 v197, v197, v150
	s_cbranch_vccz .Lres_noxb_3
	v_pk_mul_f32 v[110:111], v[110:111], v[70:71]
	v_pk_mul_f32 v[112:113], v[112:113], v[72:73]
	v_pk_mul_f32 v[106:107], v[106:107], v[66:67]
	v_pk_mul_f32 v[108:109], v[108:109], v[68:69]
	v_pk_mul_f32 v[102:103], v[102:103], v[54:55]
	v_pk_mul_f32 v[104:105], v[104:105], v[56:57]
	v_pk_mul_f32 v[98:99], v[98:99], v[50:51]
	v_pk_mul_f32 v[100:101], v[100:101], v[52:53]
	v_cvt_pk_bf16_f32 v150, v110, v111
	v_cvt_pk_bf16_f32 v151, v112, v113
	v_cvt_pk_bf16_f32 v152, v106, v107
	v_cvt_pk_bf16_f32 v153, v108, v109
	v_cvt_pk_bf16_f32 v146, v102, v103
	v_cvt_pk_bf16_f32 v147, v104, v105
	v_cvt_pk_bf16_f32 v148, v98, v99
	v_cvt_pk_bf16_f32 v149, v100, v101
	s_add_u32 s4, s62, 0x18000
	s_addc_u32 s5, s63, 0
	global_store_dwordx4 v195, v[150:153], s[4:5]
	global_store_dwordx4 v195, v[146:149], s[4:5] offset:256
; __device__ __forceinline__ unsigned cvt_pk_bf16_asm(float lo, float hi) { unsigned r; asm volatile("v_cvt_pk_bf16_f32 %0, %1, %2" : "=v"(r) : "v"(lo), "v"(hi)); return r; }
;     __device__ __forceinline__ void operator()(const f32x4 (&acc)[2][2][4][2], const Unit& u, int wr, int wc, int fr, int fq) const {
;     ...
;         for (int g8 = 0; g8 < 8; ++g8) { const int ai = g8 >> 2, m = g8 & 3;
;             ERES_LOAD(0, g8);
;             const int r = row0 + ai * HALF + m * 16; float s = 0.f;
; #pragma unroll
;             for (int bj = 0; bj < 2; ++bj) { const f32x4 x0 = xr[0][bj][0] + gv[bj][0] * acc[ai][bj][m][0], x1 = xr[0][bj][1] + gv[bj][1] * acc[ai][bj][m][1];
;                 s += (x0[0] * x0[0] + x0[1] * x0[1]) + (x0[2] * x0[2] + x0[3] * x0[3]) + (x1[0] * x1[0] + x1[1] * x1[1]) + (x1[2] * x1[2] + x1[3] * x1[3]);
;                 u32x4 w; w.x = cvt_pk_bf16_asm(x0[0], x0[1]); w.y = cvt_pk_bf16_asm(x0[2], x0[3]); w.z = cvt_pk_bf16_asm(x1[0], x1[1]); w.w = cvt_pk_bf16_asm(x1[2], x1[3]);
;                 *(u32x4*)(xh + (size_t)r * DM + col0 + bj * HALF) = w;
;                 if (xb) { const f32x4 h0 = x0 * gsv[bj][0], h1 = x1 * gsv[bj][1]; u32x4 wb; wb.x = cvt_pk_bf16_asm(h0[0], h0[1]); wb.y = cvt_pk_bf16_asm(h0[2], h0[3]); wb.z = cvt_pk_bf16_asm(h1[0], h1[1]); wb.w = cvt_pk_bf16_asm(h1[2], h1[3]);
;                     *(u32x4*)(xb + (size_t)r * DM + col0 + bj * HALF) = wb; } }
.Lres_noxb_3:
	s_waitcnt vmcnt(10)
	v_lshlrev_b32_e32 v170, 16, v142
	v_and_b32_e32 v171, 0xffff0000, v142
	v_pk_fma_f32 v[94:95], v[78:79], v[94:95], v[170:171]
	v_lshlrev_b32_e32 v172, 16, v143
	v_and_b32_e32 v173, 0xffff0000, v143
	v_pk_fma_f32 v[96:97], v[80:81], v[96:97], v[172:173]
	v_lshlrev_b32_e32 v174, 16, v144
	v_and_b32_e32 v175, 0xffff0000, v144
	v_pk_fma_f32 v[90:91], v[74:75], v[90:91], v[174:175]
	v_lshlrev_b32_e32 v176, 16, v145
	v_and_b32_e32 v177, 0xffff0000, v145
	v_pk_fma_f32 v[92:93], v[76:77], v[92:93], v[176:177]
	v_lshlrev_b32_e32 v170, 16, v138
	v_and_b32_e32 v171, 0xffff0000, v138
	v_pk_fma_f32 v[86:87], v[62:63], v[86:87], v[170:171]
	v_lshlrev_b32_e32 v172, 16, v139
	v_and_b32_e32 v173, 0xffff0000, v139
	v_pk_fma_f32 v[88:89], v[64:65], v[88:89], v[172:173]
	v_lshlrev_b32_e32 v174, 16, v140
	v_and_b32_e32 v175, 0xffff0000, v140
	v_pk_fma_f32 v[82:83], v[58:59], v[82:83], v[174:175]
	v_lshlrev_b32_e32 v176, 16, v141
	v_and_b32_e32 v177, 0xffff0000, v141
	v_pk_fma_f32 v[84:85], v[60:61], v[84:85], v[176:177]
	v_cvt_pk_bf16_f32 v170, v94, v95
	v_cvt_pk_bf16_f32 v171, v96, v97
	v_cvt_pk_bf16_f32 v172, v90, v91
	v_cvt_pk_bf16_f32 v173, v92, v93
	v_cvt_pk_bf16_f32 v174, v86, v87
	v_cvt_pk_bf16_f32 v175, v88, v89
	v_cvt_pk_bf16_f32 v176, v82, v83
	v_cvt_pk_bf16_f32 v177, v84, v85
	s_add_u32 s8, s28, 0x40000
	s_addc_u32 s9, s29, 0
	global_store_dwordx4 v195, v[170:173], s[8:9]
	global_store_dwordx4 v195, v[174:177], s[8:9] offset:256
	v_mul_f32_e32 v198, v94, v94
	v_mul_f32_e32 v142, v95, v95
	v_fmac_f32_e32 v198, v96, v96
	v_fmac_f32_e32 v142, v97, v97
	v_fmac_f32_e32 v198, v90, v90
	v_fmac_f32_e32 v142, v91, v91
	v_fmac_f32_e32 v198, v92, v92
	v_fmac_f32_e32 v142, v93, v93
	v_fmac_f32_e32 v198, v86, v86
	v_fmac_f32_e32 v142, v87, v87
	v_fmac_f32_e32 v198, v88, v88
	v_fmac_f32_e32 v142, v89, v89
	v_fmac_f32_e32 v198, v82, v82
	v_fmac_f32_e32 v142, v83, v83
	v_fmac_f32_e32 v198, v84, v84
	v_fmac_f32_e32 v142, v85, v85
	v_add_f32_e32 v198, v198, v142
	s_cbranch_vccz .Lres_noxb_4
	v_pk_mul_f32 v[94:95], v[94:95], v[70:71]
	v_pk_mul_f32 v[96:97], v[96:97], v[72:73]
	v_pk_mul_f32 v[90:91], v[90:91], v[66:67]
	v_pk_mul_f32 v[92:93], v[92:93], v[68:69]
	v_pk_mul_f32 v[86:87], v[86:87], v[54:55]
	v_pk_mul_f32 v[88:89], v[88:89], v[56:57]
	v_pk_mul_f32 v[82:83], v[82:83], v[50:51]
	v_pk_mul_f32 v[84:85], v[84:85], v[52:53]
	v_cvt_pk_bf16_f32 v142, v94, v95
	v_cvt_pk_bf16_f32 v143, v96, v97
	v_cvt_pk_bf16_f32 v144, v90, v91
	v_cvt_pk_bf16_f32 v145, v92, v93
	v_cvt_pk_bf16_f32 v138, v86, v87
	v_cvt_pk_bf16_f32 v139, v88, v89
	v_cvt_pk_bf16_f32 v140, v82, v83
	v_cvt_pk_bf16_f32 v141, v84, v85
	s_add_u32 s4, s62, 0x40000
	s_addc_u32 s5, s63, 0
	global_store_dwordx4 v195, v[142:145], s[4:5]
	global_store_dwordx4 v195, v[138:141], s[4:5] offset:256
.Lres_noxb_4:
	s_waitcnt vmcnt(10)
	v_lshlrev_b32_e32 v170, 16, v134
	v_and_b32_e32 v171, 0xffff0000, v134
	v_pk_fma_f32 v[46:47], v[78:79], v[46:47], v[170:171]
	v_lshlrev_b32_e32 v172, 16, v135
	v_and_b32_e32 v173, 0xffff0000, v135
	v_pk_fma_f32 v[48:49], v[80:81], v[48:49], v[172:173]
	v_lshlrev_b32_e32 v174, 16, v136
	v_and_b32_e32 v175, 0xffff0000, v136
	v_pk_fma_f32 v[42:43], v[74:75], v[42:43], v[174:175]
	v_lshlrev_b32_e32 v176, 16, v137
	v_and_b32_e32 v177, 0xffff0000, v137
	v_pk_fma_f32 v[44:45], v[76:77], v[44:45], v[176:177]
	v_lshlrev_b32_e32 v170, 16, v130
	v_and_b32_e32 v171, 0xffff0000, v130
	v_pk_fma_f32 v[38:39], v[62:63], v[38:39], v[170:171]
	v_lshlrev_b32_e32 v172, 16, v131
	v_and_b32_e32 v173, 0xffff0000, v131
	v_pk_fma_f32 v[40:41], v[64:65], v[40:41], v[172:173]
	v_lshlrev_b32_e32 v174, 16, v132
	v_and_b32_e32 v175, 0xffff0000, v132
	v_pk_fma_f32 v[34:35], v[58:59], v[34:35], v[174:175]
	v_lshlrev_b32_e32 v176, 16, v133
	v_and_b32_e32 v177, 0xffff0000, v133
	v_pk_fma_f32 v[36:37], v[60:61], v[36:37], v[176:177]
	v_cvt_pk_bf16_f32 v170, v46, v47
	v_cvt_pk_bf16_f32 v171, v48, v49
	v_cvt_pk_bf16_f32 v172, v42, v43
	v_cvt_pk_bf16_f32 v173, v44, v45
	v_cvt_pk_bf16_f32 v174, v38, v39
	v_cvt_pk_bf16_f32 v175, v40, v41
	v_cvt_pk_bf16_f32 v176, v34, v35
	v_cvt_pk_bf16_f32 v177, v36, v37
	s_add_u32 s8, s28, 0x48000
	s_addc_u32 s9, s29, 0
	global_store_dwordx4 v195, v[170:173], s[8:9]
	global_store_dwordx4 v195, v[174:177], s[8:9] offset:256
	v_mul_f32_e32 v199, v46, v46
	v_mul_f32_e32 v134, v47, v47
	v_fmac_f32_e32 v199, v48, v48
	v_fmac_f32_e32 v134, v49, v49
	v_fmac_f32_e32 v199, v42, v42
	v_fmac_f32_e32 v134, v43, v43
	v_fmac_f32_e32 v199, v44, v44
	v_fmac_f32_e32 v134, v45, v45
	v_fmac_f32_e32 v199, v38, v38
	v_fmac_f32_e32 v134, v39, v39
	v_fmac_f32_e32 v199, v40, v40
	v_fmac_f32_e32 v134, v41, v41
	v_fmac_f32_e32 v199, v34, v34
	v_fmac_f32_e32 v134, v35, v35
	v_fmac_f32_e32 v199, v36, v36
	v_fmac_f32_e32 v134, v37, v37
	v_add_f32_e32 v199, v199, v134
	s_cbranch_vccz .Lres_noxb_5
	v_pk_mul_f32 v[46:47], v[46:47], v[70:71]
	v_pk_mul_f32 v[48:49], v[48:49], v[72:73]
	v_pk_mul_f32 v[42:43], v[42:43], v[66:67]
	v_pk_mul_f32 v[44:45], v[44:45], v[68:69]
	v_pk_mul_f32 v[38:39], v[38:39], v[54:55]
	v_pk_mul_f32 v[40:41], v[40:41], v[56:57]
	v_pk_mul_f32 v[34:35], v[34:35], v[50:51]
	v_pk_mul_f32 v[36:37], v[36:37], v[52:53]
	v_cvt_pk_bf16_f32 v134, v46, v47
	v_cvt_pk_bf16_f32 v135, v48, v49
	v_cvt_pk_bf16_f32 v136, v42, v43
	v_cvt_pk_bf16_f32 v137, v44, v45
	v_cvt_pk_bf16_f32 v130, v38, v39
	v_cvt_pk_bf16_f32 v131, v40, v41
	v_cvt_pk_bf16_f32 v132, v34, v35
	v_cvt_pk_bf16_f32 v133, v36, v37
	s_add_u32 s4, s62, 0x48000
	s_addc_u32 s5, s63, 0
	global_store_dwordx4 v195, v[134:137], s[4:5]
	global_store_dwordx4 v195, v[130:133], s[4:5] offset:256
; __device__ __forceinline__ unsigned cvt_pk_bf16_asm(float lo, float hi) { unsigned r; asm volatile("v_cvt_pk_bf16_f32 %0, %1, %2" : "=v"(r) : "v"(lo), "v"(hi)); return r; }
;     __device__ __forceinline__ void operator()(const f32x4 (&acc)[2][2][4][2], const Unit& u, int wr, int wc, int fr, int fq) const {
;     ...
;         for (int g8 = 0; g8 < 8; ++g8) { const int ai = g8 >> 2, m = g8 & 3;
;             ERES_LOAD(0, g8);
;             const int r = row0 + ai * HALF + m * 16; float s = 0.f;
; #pragma unroll
;             for (int bj = 0; bj < 2; ++bj) { const f32x4 x0 = xr[0][bj][0] + gv[bj][0] * acc[ai][bj][m][0], x1 = xr[0][bj][1] + gv[bj][1] * acc[ai][bj][m][1];
;                 s += (x0[0] * x0[0] + x0[1] * x0[1]) + (x0[2] * x0[2] + x0[3] * x0[3]) + (x1[0] * x1[0] + x1[1] * x1[1]) + (x1[2] * x1[2] + x1[3] * x1[3]);
;                 u32x4 w; w.x = cvt_pk_bf16_asm(x0[0], x0[1]); w.y = cvt_pk_bf16_asm(x0[2], x0[3]); w.z = cvt_pk_bf16_asm(x1[0], x1[1]); w.w = cvt_pk_bf16_asm(x1[2], x1[3]);
;                 *(u32x4*)(xh + (size_t)r * DM + col0 + bj * HALF) = w;
;                 if (xb) { const f32x4 h0 = x0 * gsv[bj][0], h1 = x1 * gsv[bj][1]; u32x4 wb; wb.x = cvt_pk_bf16_asm(h0[0], h0[1]); wb.y = cvt_pk_bf16_asm(h0[2], h0[3]); wb.z = cvt_pk_bf16_asm(h1[0], h1[1]); wb.w = cvt_pk_bf16_asm(h1[2], h1[3]);
;                     *(u32x4*)(xb + (size_t)r * DM + col0 + bj * HALF) = wb; } }
.Lres_noxb_5:
	s_waitcnt vmcnt(8)
	v_lshlrev_b32_e32 v170, 16, v126
	v_and_b32_e32 v171, 0xffff0000, v126
	v_pk_fma_f32 v[30:31], v[78:79], v[30:31], v[170:171]
	v_lshlrev_b32_e32 v172, 16, v127
	v_and_b32_e32 v173, 0xffff0000, v127
	v_pk_fma_f32 v[32:33], v[80:81], v[32:33], v[172:173]
	v_lshlrev_b32_e32 v174, 16, v128
	v_and_b32_e32 v175, 0xffff0000, v128
	v_pk_fma_f32 v[26:27], v[74:75], v[26:27], v[174:175]
	v_lshlrev_b32_e32 v176, 16, v129
	v_and_b32_e32 v177, 0xffff0000, v129
	v_pk_fma_f32 v[28:29], v[76:77], v[28:29], v[176:177]
	v_lshlrev_b32_e32 v170, 16, v122
	v_and_b32_e32 v171, 0xffff0000, v122
	v_pk_fma_f32 v[22:23], v[62:63], v[22:23], v[170:171]
	v_lshlrev_b32_e32 v172, 16, v123
	v_and_b32_e32 v173, 0xffff0000, v123
	v_pk_fma_f32 v[24:25], v[64:65], v[24:25], v[172:173]
	v_lshlrev_b32_e32 v174, 16, v124
	v_and_b32_e32 v175, 0xffff0000, v124
	v_pk_fma_f32 v[18:19], v[58:59], v[18:19], v[174:175]
	v_lshlrev_b32_e32 v176, 16, v125
	v_and_b32_e32 v177, 0xffff0000, v125
	v_pk_fma_f32 v[20:21], v[60:61], v[20:21], v[176:177]
	v_cvt_pk_bf16_f32 v170, v30, v31
	v_cvt_pk_bf16_f32 v171, v32, v33
	v_cvt_pk_bf16_f32 v172, v26, v27
	v_cvt_pk_bf16_f32 v173, v28, v29
	v_cvt_pk_bf16_f32 v174, v22, v23
	v_cvt_pk_bf16_f32 v175, v24, v25
	v_cvt_pk_bf16_f32 v176, v18, v19
	v_cvt_pk_bf16_f32 v177, v20, v21
	s_add_u32 s8, s28, 0x50000
	s_addc_u32 s9, s29, 0
	global_store_dwordx4 v195, v[170:173], s[8:9]
	global_store_dwordx4 v195, v[174:177], s[8:9] offset:256
	v_mul_f32_e32 v202, v30, v30
	v_mul_f32_e32 v126, v31, v31
	v_fmac_f32_e32 v202, v32, v32
	v_fmac_f32_e32 v126, v33, v33
	v_fmac_f32_e32 v202, v26, v26
	v_fmac_f32_e32 v126, v27, v27
	v_fmac_f32_e32 v202, v28, v28
	v_fmac_f32_e32 v126, v29, v29
	v_fmac_f32_e32 v202, v22, v22
	v_fmac_f32_e32 v126, v23, v23
	v_fmac_f32_e32 v202, v24, v24
	v_fmac_f32_e32 v126, v25, v25
	v_fmac_f32_e32 v202, v18, v18
	v_fmac_f32_e32 v126, v19, v19
	v_fmac_f32_e32 v202, v20, v20
	v_fmac_f32_e32 v126, v21, v21
	v_add_f32_e32 v202, v202, v126
	s_cbranch_vccz .Lres_noxb_6
	v_pk_mul_f32 v[30:31], v[30:31], v[70:71]
	v_pk_mul_f32 v[32:33], v[32:33], v[72:73]
	v_pk_mul_f32 v[26:27], v[26:27], v[66:67]
	v_pk_mul_f32 v[28:29], v[28:29], v[68:69]
	v_pk_mul_f32 v[22:23], v[22:23], v[54:55]
	v_pk_mul_f32 v[24:25], v[24:25], v[56:57]
	v_pk_mul_f32 v[18:19], v[18:19], v[50:51]
	v_pk_mul_f32 v[20:21], v[20:21], v[52:53]
	v_cvt_pk_bf16_f32 v126, v30, v31
	v_cvt_pk_bf16_f32 v127, v32, v33
	v_cvt_pk_bf16_f32 v128, v26, v27
	v_cvt_pk_bf16_f32 v129, v28, v29
	v_cvt_pk_bf16_f32 v122, v22, v23
	v_cvt_pk_bf16_f32 v123, v24, v25
	v_cvt_pk_bf16_f32 v124, v18, v19
	v_cvt_pk_bf16_f32 v125, v20, v21
	s_add_u32 s4, s62, 0x50000
	s_addc_u32 s5, s63, 0
	global_store_dwordx4 v195, v[126:129], s[4:5]
	global_store_dwordx4 v195, v[122:125], s[4:5] offset:256
.Lres_noxb_6:
	s_waitcnt vmcnt(8)
	v_lshlrev_b32_e32 v170, 16, v118
	v_and_b32_e32 v171, 0xffff0000, v118
	v_pk_fma_f32 v[14:15], v[78:79], v[14:15], v[170:171]
	v_lshlrev_b32_e32 v172, 16, v119
	v_and_b32_e32 v173, 0xffff0000, v119
	v_pk_fma_f32 v[16:17], v[80:81], v[16:17], v[172:173]
	v_lshlrev_b32_e32 v174, 16, v120
	v_and_b32_e32 v175, 0xffff0000, v120
	v_pk_fma_f32 v[10:11], v[74:75], v[10:11], v[174:175]
	v_lshlrev_b32_e32 v176, 16, v121
	v_and_b32_e32 v177, 0xffff0000, v121
	v_pk_fma_f32 v[12:13], v[76:77], v[12:13], v[176:177]
	v_lshlrev_b32_e32 v170, 16, v114
	v_and_b32_e32 v171, 0xffff0000, v114
	v_pk_fma_f32 v[6:7], v[62:63], v[6:7], v[170:171]
	v_lshlrev_b32_e32 v172, 16, v115
	v_and_b32_e32 v173, 0xffff0000, v115
	v_pk_fma_f32 v[8:9], v[64:65], v[8:9], v[172:173]
	v_lshlrev_b32_e32 v174, 16, v116
	v_and_b32_e32 v175, 0xffff0000, v116
	v_pk_fma_f32 v[2:3], v[58:59], v[2:3], v[174:175]
	v_lshlrev_b32_e32 v176, 16, v117
	v_and_b32_e32 v177, 0xffff0000, v117
	v_pk_fma_f32 v[4:5], v[60:61], v[4:5], v[176:177]
	v_cvt_pk_bf16_f32 v170, v14, v15
	v_cvt_pk_bf16_f32 v171, v16, v17
	v_cvt_pk_bf16_f32 v172, v10, v11
	v_cvt_pk_bf16_f32 v173, v12, v13
	v_cvt_pk_bf16_f32 v174, v6, v7
	v_cvt_pk_bf16_f32 v175, v8, v9
	v_cvt_pk_bf16_f32 v176, v2, v3
	v_cvt_pk_bf16_f32 v177, v4, v5
	s_add_u32 s8, s28, 0x58000
	s_addc_u32 s9, s29, 0
	global_store_dwordx4 v195, v[170:173], s[8:9]
	global_store_dwordx4 v195, v[174:177], s[8:9] offset:256
	v_mul_f32_e32 v203, v14, v14
	v_mul_f32_e32 v118, v15, v15
	v_fmac_f32_e32 v203, v16, v16
	v_fmac_f32_e32 v118, v17, v17
	v_fmac_f32_e32 v203, v10, v10
	v_fmac_f32_e32 v118, v11, v11
	v_fmac_f32_e32 v203, v12, v12
	v_fmac_f32_e32 v118, v13, v13
	v_fmac_f32_e32 v203, v6, v6
	v_fmac_f32_e32 v118, v7, v7
	v_fmac_f32_e32 v203, v8, v8
	v_fmac_f32_e32 v118, v9, v9
	v_fmac_f32_e32 v203, v2, v2
	v_fmac_f32_e32 v118, v3, v3
	v_fmac_f32_e32 v203, v4, v4
	v_fmac_f32_e32 v118, v5, v5
	v_add_f32_e32 v203, v203, v118
	s_cbranch_vccz .Lres_noxb_7
	v_pk_mul_f32 v[14:15], v[14:15], v[70:71]
	v_pk_mul_f32 v[16:17], v[16:17], v[72:73]
	v_pk_mul_f32 v[10:11], v[10:11], v[66:67]
	v_pk_mul_f32 v[12:13], v[12:13], v[68:69]
	v_pk_mul_f32 v[6:7], v[6:7], v[54:55]
	v_pk_mul_f32 v[8:9], v[8:9], v[56:57]
	v_pk_mul_f32 v[2:3], v[2:3], v[50:51]
	v_pk_mul_f32 v[4:5], v[4:5], v[52:53]
	v_cvt_pk_bf16_f32 v118, v14, v15
	v_cvt_pk_bf16_f32 v119, v16, v17
	v_cvt_pk_bf16_f32 v120, v10, v11
	v_cvt_pk_bf16_f32 v121, v12, v13
	v_cvt_pk_bf16_f32 v114, v6, v7
	v_cvt_pk_bf16_f32 v115, v8, v9
	v_cvt_pk_bf16_f32 v116, v2, v3
	v_cvt_pk_bf16_f32 v117, v4, v5
	s_add_u32 s4, s62, 0x58000
	s_addc_u32 s5, s63, 0
	global_store_dwordx4 v195, v[118:121], s[4:5]
	global_store_dwordx4 v195, v[114:117], s[4:5] offset:256
;     __device__ __forceinline__ void operator()(const f32x4 (&acc)[2][2][4][2], const Unit& u, int wr, int wc, int fr, int fq) const {
;     ...
;             s += __shfl_xor(s, 16); s += __shfl_xor(s, 32); if (fq == 0) (void)__hip_atomic_fetch_add(ssn + r, (u64)(s * SSK), __ATOMIC_RELAXED, __HIP_MEMORY_SCOPE_AGENT);
.Lres_noxb_7:
	v_mov_b32_e32 v2, v192
	v_mov_b32_e32 v6, v194
	v_mov_b32_e32 v10, v196
	v_mov_b32_e32 v14, v197
	v_mov_b32_e32 v18, v198
	v_mov_b32_e32 v22, v199
	v_mov_b32_e32 v26, v202
	v_mov_b32_e32 v34, v203
	s_nop 1
	v_permlane32_swap_b32_e32 v192, v2
	v_permlane32_swap_b32_e32 v194, v6
	v_permlane32_swap_b32_e32 v196, v10
	v_permlane32_swap_b32_e32 v197, v14
	v_permlane32_swap_b32_e32 v198, v18
	v_permlane32_swap_b32_e32 v199, v22
	v_permlane32_swap_b32_e32 v202, v26
	v_permlane32_swap_b32_e32 v203, v34
	v_add_f32_e32 v192, v192, v2
	v_add_f32_e32 v194, v194, v6
	v_add_f32_e32 v196, v196, v10
	v_add_f32_e32 v197, v197, v14
	v_add_f32_e32 v198, v198, v18
	v_add_f32_e32 v199, v199, v22
	v_add_f32_e32 v202, v202, v26
	v_add_f32_e32 v203, v203, v34
	v_mov_b32_e32 v2, v192
	v_mov_b32_e32 v6, v194
	v_mov_b32_e32 v10, v196
	v_mov_b32_e32 v14, v197
	v_mov_b32_e32 v18, v198
	v_mov_b32_e32 v22, v199
	v_mov_b32_e32 v26, v202
	v_mov_b32_e32 v34, v203
	s_nop 1
	v_permlane16_swap_b32_e32 v192, v2
	v_permlane16_swap_b32_e32 v194, v6
	v_permlane16_swap_b32_e32 v196, v10
	v_permlane16_swap_b32_e32 v197, v14
	v_permlane16_swap_b32_e32 v198, v18
	v_permlane16_swap_b32_e32 v199, v22
	v_permlane16_swap_b32_e32 v202, v26
	v_permlane16_swap_b32_e32 v203, v34
	v_add_f32_e32 v192, v192, v2
	v_add_f32_e32 v194, v194, v6
	v_add_f32_e32 v196, v196, v10
	v_add_f32_e32 v197, v197, v14
	v_add_f32_e32 v198, v198, v18
	v_add_f32_e32 v199, v199, v22
	v_add_f32_e32 v202, v202, v26
	v_add_f32_e32 v203, v203, v34
	s_mov_b64 exec, 0xffff
	v_mul_f32_e32 v38, 0x49800000, v192
	v_trunc_f32_e32 v38, v38
	v_mul_f32_e32 v39, 0x2f800000, v38
	v_floor_f32_e32 v39, v39
	v_fmac_f32_e32 v38, 0xcf800000, v39
	v_cvt_u32_f32_e32 v38, v38
	v_cvt_u32_f32_e32 v39, v39
	v_mul_f32_e32 v42, 0x49800000, v194
	v_trunc_f32_e32 v42, v42
	v_mul_f32_e32 v43, 0x2f800000, v42
	v_floor_f32_e32 v43, v43
	v_fmac_f32_e32 v42, 0xcf800000, v43
	v_cvt_u32_f32_e32 v42, v42
	v_cvt_u32_f32_e32 v43, v43
	v_mul_f32_e32 v46, 0x49800000, v196
	v_trunc_f32_e32 v46, v46
	v_mul_f32_e32 v47, 0x2f800000, v46
	v_floor_f32_e32 v47, v47
	v_fmac_f32_e32 v46, 0xcf800000, v47
	v_cvt_u32_f32_e32 v46, v46
	v_cvt_u32_f32_e32 v47, v47
	v_mul_f32_e32 v82, 0x49800000, v197
	v_trunc_f32_e32 v82, v82
	v_mul_f32_e32 v83, 0x2f800000, v82
	v_floor_f32_e32 v83, v83
	v_fmac_f32_e32 v82, 0xcf800000, v83
	v_cvt_u32_f32_e32 v82, v82
	v_cvt_u32_f32_e32 v83, v83
	v_mul_f32_e32 v86, 0x49800000, v198
	v_trunc_f32_e32 v86, v86
	v_mul_f32_e32 v87, 0x2f800000, v86
	v_floor_f32_e32 v87, v87
	v_fmac_f32_e32 v86, 0xcf800000, v87
	v_cvt_u32_f32_e32 v86, v86
	v_cvt_u32_f32_e32 v87, v87
	v_mul_f32_e32 v90, 0x49800000, v199
	v_trunc_f32_e32 v90, v90
	v_mul_f32_e32 v91, 0x2f800000, v90
	v_floor_f32_e32 v91, v91
	v_fmac_f32_e32 v90, 0xcf800000, v91
	v_cvt_u32_f32_e32 v90, v90
	v_cvt_u32_f32_e32 v91, v91
	v_mul_f32_e32 v94, 0x49800000, v202
	v_trunc_f32_e32 v94, v94
	v_mul_f32_e32 v95, 0x2f800000, v94
	v_floor_f32_e32 v95, v95
	v_fmac_f32_e32 v94, 0xcf800000, v95
	v_cvt_u32_f32_e32 v94, v94
	v_cvt_u32_f32_e32 v95, v95
	v_mul_f32_e32 v98, 0x49800000, v203
	v_trunc_f32_e32 v98, v98
	v_mul_f32_e32 v99, 0x2f800000, v98
	v_floor_f32_e32 v99, v99
	v_fmac_f32_e32 v98, 0xcf800000, v99
	v_cvt_u32_f32_e32 v98, v98
	v_cvt_u32_f32_e32 v99, v99
	global_atomic_add_x2 v193, v[38:39], s[88:89]
	global_atomic_add_x2 v193, v[42:43], s[88:89] offset:128
	global_atomic_add_x2 v193, v[46:47], s[88:89] offset:256
	global_atomic_add_x2 v193, v[82:83], s[88:89] offset:384
	global_atomic_add_x2 v193, v[86:87], s[88:89] offset:1024
	global_atomic_add_x2 v193, v[90:91], s[88:89] offset:1152
	global_atomic_add_x2 v193, v[94:95], s[88:89] offset:1280
	global_atomic_add_x2 v193, v[98:99], s[88:89] offset:1408
	s_mov_b64 exec, -1
	s_branch .LBB0_649
